# EPI_F32 GEMM: swapped MFMA operands + LDS-staged whole-row dwordx4 epilogue stores; REC_IN tile rotation; K-loop vmcnt(0) drains removed
# speedup vs baseline: 1.0640x; 1.0212x over previous
; #define STAGE(bufoff, GB) do { const char* g_ = (GB); \
;         _Pragma("unroll") for (int i_ = 0; i_ < 2; ++i_) __builtin_amdgcn_global_load_lds((const unsigned*)(g_ + voff[i_]), (LAS3 unsigned*)(L + (bufoff) + stoff + i_ * 8192), 16, 0, 0); } while (0)
; #define LDA(dst, b, h) do { _Pragma("unroll") for (int m = 0; m < 4; ++m) _Pragma("unroll") for (int k = 0; k < 2; ++k) dst[m][k] = *(const LAS3 bf16x8*)(L + SA(b, h) + aoff + m * 2048 + k * 1024); } while (0)
; #define LDB(dst, b, h) do { _Pragma("unroll") for (int n = 0; n < 2; ++n) _Pragma("unroll") for (int k = 0; k < 2; ++k) dst[n][k] = *(const LAS3 bf16x8*)(L + SB(b, h) + boff + n * 2048 + k * 1024); } while (0)
; #define WAIT_V(n) asm volatile("s_waitcnt vmcnt(" #n ")" ::: "memory")
; #define WAIT_L(n) asm volatile("s_waitcnt lgkmcnt(" #n ")" ::: "memory")
; #define BAR __builtin_amdgcn_s_barrier()
; #define SCHED __builtin_amdgcn_sched_barrier(0)
; template <int EPI>
; DI void gemm_phase(const bf16_t* __restrict__ A, const bf16_t* __restrict__ Bt, const int K, const int N, const Params& p, const int layer_j, char* lds) {
;     ...
;         for (int t = 0; t < nt; t += 2) {
;             const bool last = (t == nt - 2);
;             const char* a1 = cA + (size_t)(t + 1) * kstep;
;             const char* a2 = last ? nA : cA + (size_t)(t + 2) * kstep; const char* b2 = last ? nB : cB + (size_t)(t + 2) * kstep;
;             const char* a3 = a2 + kstep; const char* b3 = b2 + kstep;
;             LDB(B0, 0, 0); LDB(B1, 0, 1); SCHED; LDA(At, 0, 0); STAGE(SA(1, 1), a1 + hstep);
;             WAIT_V(8); WAIT_L(0); BAR; MMA(0, 0, At, B0); MMA(0, 1, At, B1); BAR; SCHED;
;             LDA(At, 0, 1); STAGE(SB(0, 0), b2); STAGE(SB(0, 1), b2 + hstep); STAGE(SA(0, 0), a2);
;             WAIT_V(8); WAIT_L(0); BAR; MMA(1, 0, At, B0); MMA(1, 1, At, B1); BAR; SCHED;
.LBB0_106:
	v_add_u32_e32 v164, 0x10000, v138
	v_add_u32_e32 v180, 0x14000, v138
	ds_read_b128 v[152:155], v164
	ds_read_b128 v[156:159], v164 offset:1024
	ds_read_b128 v[160:163], v164 offset:2048
	ds_read_b128 v[164:167], v164 offset:3072
	ds_read_b128 v[168:171], v180
	ds_read_b128 v[172:175], v180 offset:1024
	ds_read_b128 v[176:179], v180 offset:2048
	ds_read_b128 v[180:183], v180 offset:3072
	s_add_i32 s39, s18, 2
	s_add_u32 s64, s16, 0x80
	s_addc_u32 s19, s17, 0
	s_cmp_eq_u32 s25, s18
	s_cselect_b32 s18, s14, s64
	s_cselect_b32 s19, s15, s19
	s_cselect_b32 s65, s36, s38
	s_cselect_b32 s64, s35, s37
	v_add_u32_e32 v194, 0xc000, v136
	v_lshl_add_u64 v[192:193], s[16:17], 0, v[134:135]
	v_readfirstlane_b32 s66, v194
	v_add_u32_e32 v194, 0xe000, v136
	s_mov_b32 m0, s66
	v_readfirstlane_b32 s66, v194
	ds_read_b128 v[184:187], v137
	ds_read_b128 v[188:191], v137 offset:1024
	ds_read_b128 v[204:207], v137 offset:2048
	ds_read_b128 v[208:211], v137 offset:3072
	ds_read_b128 v[212:215], v137 offset:4096
	ds_read_b128 v[216:219], v137 offset:5120
	ds_read_b128 v[220:223], v137 offset:6144
	ds_read_b128 v[224:227], v137 offset:7168
	global_load_lds_dwordx4 v[192:193], off
	v_lshl_add_u64 v[192:193], s[16:17], 0, v[132:133]
	s_mov_b32 m0, s66
	s_nop 0
	global_load_lds_dwordx4 v[192:193], off
	s_waitcnt vmcnt(8)
	s_waitcnt lgkmcnt(0)
	s_barrier
	s_setprio 1
	s_waitcnt lgkmcnt(0)
	v_mfma_f32_16x16x32_bf16 v[126:129], v[152:155], v[184:187], v[126:129]
	v_mfma_f32_16x16x32_bf16 v[122:125], v[160:163], v[184:187], v[122:125]
	v_mfma_f32_16x16x32_bf16 v[110:113], v[152:155], v[204:207], v[110:113]
	v_mfma_f32_16x16x32_bf16 v[106:109], v[160:163], v[204:207], v[106:109]
	v_mfma_f32_16x16x32_bf16 v[94:97], v[152:155], v[212:215], v[94:97]
	v_mfma_f32_16x16x32_bf16 v[90:93], v[160:163], v[212:215], v[90:93]
	v_mfma_f32_16x16x32_bf16 v[78:81], v[152:155], v[220:223], v[78:81]
	v_mfma_f32_16x16x32_bf16 v[74:77], v[160:163], v[220:223], v[74:77]
	v_mfma_f32_16x16x32_bf16 v[126:129], v[156:159], v[188:191], v[126:129]
	v_mfma_f32_16x16x32_bf16 v[122:125], v[164:167], v[188:191], v[122:125]
	v_mfma_f32_16x16x32_bf16 v[110:113], v[156:159], v[208:211], v[110:113]
	v_mfma_f32_16x16x32_bf16 v[106:109], v[164:167], v[208:211], v[106:109]
	v_mfma_f32_16x16x32_bf16 v[94:97], v[156:159], v[216:219], v[94:97]
	v_mfma_f32_16x16x32_bf16 v[90:93], v[164:167], v[216:219], v[90:93]
	v_mfma_f32_16x16x32_bf16 v[78:81], v[156:159], v[224:227], v[78:81]
	v_mfma_f32_16x16x32_bf16 v[74:77], v[164:167], v[224:227], v[74:77]
	s_setprio 0
	s_setprio 1
	v_mfma_f32_16x16x32_bf16 v[118:121], v[168:171], v[184:187], v[118:121]
	v_mfma_f32_16x16x32_bf16 v[114:117], v[176:179], v[184:187], v[114:117]
	v_mfma_f32_16x16x32_bf16 v[102:105], v[168:171], v[204:207], v[102:105]
	v_mfma_f32_16x16x32_bf16 v[98:101], v[176:179], v[204:207], v[98:101]
	v_mfma_f32_16x16x32_bf16 v[86:89], v[168:171], v[212:215], v[86:89]
	v_mfma_f32_16x16x32_bf16 v[82:85], v[176:179], v[212:215], v[82:85]
	v_mfma_f32_16x16x32_bf16 v[70:73], v[168:171], v[220:223], v[70:73]
	v_mfma_f32_16x16x32_bf16 v[66:69], v[176:179], v[220:223], v[66:69]
	v_mfma_f32_16x16x32_bf16 v[118:121], v[172:175], v[188:191], v[118:121]
	v_mfma_f32_16x16x32_bf16 v[114:117], v[180:183], v[188:191], v[114:117]
	v_mfma_f32_16x16x32_bf16 v[102:105], v[172:175], v[208:211], v[102:105]
	v_mfma_f32_16x16x32_bf16 v[98:101], v[180:183], v[208:211], v[98:101]
	v_mfma_f32_16x16x32_bf16 v[86:89], v[172:175], v[216:219], v[86:89]
	v_mfma_f32_16x16x32_bf16 v[82:85], v[180:183], v[216:219], v[82:85]
	v_mfma_f32_16x16x32_bf16 v[70:73], v[172:175], v[224:227], v[70:73]
	v_mfma_f32_16x16x32_bf16 v[66:69], v[180:183], v[224:227], v[66:69]
	s_setprio 0
	s_barrier
	v_readfirstlane_b32 s66, v139
	v_lshl_add_u64 v[192:193], s[64:65], 0, v[32:33]
	s_mov_b32 m0, s66
	v_lshl_add_u64 v[194:195], s[64:65], 0, v[130:131]
	v_readfirstlane_b32 s66, v140
	s_add_u32 s64, s64, s88
	ds_read_b128 v[184:187], v137 offset:16384
	ds_read_b128 v[188:191], v137 offset:17408
	ds_read_b128 v[204:207], v137 offset:18432
	ds_read_b128 v[208:211], v137 offset:19456
	ds_read_b128 v[212:215], v137 offset:20480
	ds_read_b128 v[216:219], v137 offset:21504
	ds_read_b128 v[220:223], v137 offset:22528
	ds_read_b128 v[224:227], v137 offset:23552
	global_load_lds_dwordx4 v[192:193], off
	s_mov_b32 m0, s66
	s_addc_u32 s65, s65, 0
	v_readfirstlane_b32 s66, v141
	global_load_lds_dwordx4 v[194:195], off
	v_lshl_add_u64 v[228:229], s[64:65], 0, v[32:33]
	s_mov_b32 m0, s66
	v_lshl_add_u64 v[230:231], s[64:65], 0, v[130:131]
	v_readfirstlane_b32 s64, v142
	global_load_lds_dwordx4 v[228:229], off
	s_mov_b32 m0, s64
	v_readfirstlane_b32 s64, v136
	global_load_lds_dwordx4 v[230:231], off
	v_lshl_add_u64 v[232:233], s[18:19], 0, v[32:33]
	s_mov_b32 m0, s64
	v_readfirstlane_b32 s64, v143
	global_load_lds_dwordx4 v[232:233], off
	v_lshl_add_u64 v[234:235], s[18:19], 0, v[130:131]
	s_mov_b32 m0, s64
	s_nop 0
	global_load_lds_dwordx4 v[234:235], off
	s_waitcnt vmcnt(8)
	s_waitcnt lgkmcnt(0)
	s_barrier
; #define STAGE(bufoff, GB) do { const char* g_ = (GB); \
;         _Pragma("unroll") for (int i_ = 0; i_ < 2; ++i_) __builtin_amdgcn_global_load_lds((const unsigned*)(g_ + voff[i_]), (LAS3 unsigned*)(L + (bufoff) + stoff + i_ * 8192), 16, 0, 0); } while (0)
; #define LDA(dst, b, h) do { _Pragma("unroll") for (int m = 0; m < 4; ++m) _Pragma("unroll") for (int k = 0; k < 2; ++k) dst[m][k] = *(const LAS3 bf16x8*)(L + SA(b, h) + aoff + m * 2048 + k * 1024); } while (0)
; #define LDB(dst, b, h) do { _Pragma("unroll") for (int n = 0; n < 2; ++n) _Pragma("unroll") for (int k = 0; k < 2; ++k) dst[n][k] = *(const LAS3 bf16x8*)(L + SB(b, h) + boff + n * 2048 + k * 1024); } while (0)
; #define WAIT_V(n) asm volatile("s_waitcnt vmcnt(" #n ")" ::: "memory")
; #define WAIT_L(n) asm volatile("s_waitcnt lgkmcnt(" #n ")" ::: "memory")
; #define BAR __builtin_amdgcn_s_barrier()
; #define SCHED __builtin_amdgcn_sched_barrier(0)
; template <int EPI>
; DI void gemm_phase(const bf16_t* __restrict__ A, const bf16_t* __restrict__ Bt, const int K, const int N, const Params& p, const int layer_j, char* lds) {
;     ...
;             WAIT_V(8); WAIT_L(0); BAR; MMA(1, 0, At, B0); MMA(1, 1, At, B1); BAR; SCHED;
;             LDB(B0, 1, 0); LDB(B1, 1, 1); SCHED; LDA(At, 1, 0); STAGE(SA(0, 1), a2 + hstep);
;             WAIT_V(8); WAIT_L(0); BAR; MMA(0, 0, At, B0); MMA(0, 1, At, B1); BAR; SCHED;
;             LDA(At, 1, 1); STAGE(SB(1, 0), b3); STAGE(SB(1, 1), b3 + hstep); STAGE(SA(1, 0), a3);
;             WAIT_V(8); WAIT_L(0); BAR; MMA(1, 0, At, B0); MMA(1, 1, At, B1); BAR; SCHED;
	s_setprio 1
	s_waitcnt lgkmcnt(0)
	v_mfma_f32_16x16x32_bf16 v[62:65], v[152:155], v[184:187], v[62:65]
	v_mfma_f32_16x16x32_bf16 v[58:61], v[160:163], v[184:187], v[58:61]
	v_mfma_f32_16x16x32_bf16 v[38:41], v[152:155], v[204:207], v[38:41]
	v_mfma_f32_16x16x32_bf16 v[24:27], v[160:163], v[204:207], v[24:27]
	v_mfma_f32_16x16x32_bf16 v[12:15], v[152:155], v[212:215], v[12:15]
	v_mfma_f32_16x16x32_bf16 v[8:11], v[160:163], v[212:215], v[8:11]
	v_mfma_f32_16x16x32_bf16 v[4:7], v[152:155], v[220:223], v[4:7]
	v_mfma_f32_16x16x32_bf16 v[0:3], v[160:163], v[220:223], v[0:3]
	v_mfma_f32_16x16x32_bf16 v[62:65], v[156:159], v[188:191], v[62:65]
	v_mfma_f32_16x16x32_bf16 v[58:61], v[164:167], v[188:191], v[58:61]
	v_mfma_f32_16x16x32_bf16 v[38:41], v[156:159], v[208:211], v[38:41]
	v_mfma_f32_16x16x32_bf16 v[24:27], v[164:167], v[208:211], v[24:27]
	v_mfma_f32_16x16x32_bf16 v[12:15], v[156:159], v[216:219], v[12:15]
	v_mfma_f32_16x16x32_bf16 v[8:11], v[164:167], v[216:219], v[8:11]
	v_mfma_f32_16x16x32_bf16 v[4:7], v[156:159], v[224:227], v[4:7]
	v_mfma_f32_16x16x32_bf16 v[0:3], v[164:167], v[224:227], v[0:3]
	s_setprio 0
	s_setprio 1
	v_mfma_f32_16x16x32_bf16 v[46:49], v[168:171], v[184:187], v[46:49]
	v_mfma_f32_16x16x32_bf16 v[42:45], v[176:179], v[184:187], v[42:45]
	v_mfma_f32_16x16x32_bf16 v[20:23], v[168:171], v[204:207], v[20:23]
	v_mfma_f32_16x16x32_bf16 v[16:19], v[176:179], v[204:207], v[16:19]
	v_mfma_f32_16x16x32_bf16 v[50:53], v[168:171], v[212:215], v[50:53]
	v_mfma_f32_16x16x32_bf16 v[54:57], v[176:179], v[212:215], v[54:57]
	v_mfma_f32_16x16x32_bf16 v[28:31], v[168:171], v[220:223], v[28:31]
	v_mfma_f32_16x16x32_bf16 v[34:37], v[176:179], v[220:223], v[34:37]
	v_mfma_f32_16x16x32_bf16 v[46:49], v[172:175], v[188:191], v[46:49]
	v_mfma_f32_16x16x32_bf16 v[42:45], v[180:183], v[188:191], v[42:45]
	v_mfma_f32_16x16x32_bf16 v[20:23], v[172:175], v[208:211], v[20:23]
	v_mfma_f32_16x16x32_bf16 v[16:19], v[180:183], v[208:211], v[16:19]
	v_mfma_f32_16x16x32_bf16 v[50:53], v[172:175], v[216:219], v[50:53]
	v_mfma_f32_16x16x32_bf16 v[54:57], v[180:183], v[216:219], v[54:57]
	v_mfma_f32_16x16x32_bf16 v[28:31], v[172:175], v[224:227], v[28:31]
	v_mfma_f32_16x16x32_bf16 v[34:37], v[180:183], v[224:227], v[34:37]
	s_setprio 0
	s_barrier
	v_add_u32_e32 v164, 0x18000, v138
	v_add_u32_e32 v180, 0x1c000, v138
	ds_read_b128 v[152:155], v164
	ds_read_b128 v[156:159], v164 offset:1024
	ds_read_b128 v[160:163], v164 offset:2048
	ds_read_b128 v[164:167], v164 offset:3072
	ds_read_b128 v[168:171], v180
	ds_read_b128 v[172:175], v180 offset:1024
	ds_read_b128 v[176:179], v180 offset:2048
	ds_read_b128 v[180:183], v180 offset:3072
	s_add_u32 s18, s18, s88
	s_addc_u32 s19, s19, 0
	v_readfirstlane_b32 s64, v144
	v_lshl_add_u64 v[236:237], s[18:19], 0, v[32:33]
	s_mov_b32 m0, s64
	ds_read_b128 v[184:187], v137 offset:32768
	ds_read_b128 v[188:191], v137 offset:33792
	ds_read_b128 v[204:207], v137 offset:34816
	ds_read_b128 v[208:211], v137 offset:35840
	ds_read_b128 v[212:215], v137 offset:36864
	ds_read_b128 v[216:219], v137 offset:37888
	ds_read_b128 v[220:223], v137 offset:38912
	ds_read_b128 v[224:227], v137 offset:39936
	global_load_lds_dwordx4 v[236:237], off
	v_lshl_add_u64 v[236:237], s[18:19], 0, v[130:131]
	v_readfirstlane_b32 s18, v145
	s_mov_b32 m0, s18
	s_nop 0
	global_load_lds_dwordx4 v[236:237], off
	s_waitcnt vmcnt(8)
	s_waitcnt lgkmcnt(0)
	s_barrier
	s_setprio 1
	s_waitcnt lgkmcnt(0)
	v_mfma_f32_16x16x32_bf16 v[126:129], v[152:155], v[184:187], v[126:129]
	v_mfma_f32_16x16x32_bf16 v[122:125], v[160:163], v[184:187], v[122:125]
	v_mfma_f32_16x16x32_bf16 v[110:113], v[152:155], v[204:207], v[110:113]
	v_mfma_f32_16x16x32_bf16 v[106:109], v[160:163], v[204:207], v[106:109]
	v_mfma_f32_16x16x32_bf16 v[94:97], v[152:155], v[212:215], v[94:97]
	v_mfma_f32_16x16x32_bf16 v[90:93], v[160:163], v[212:215], v[90:93]
	v_mfma_f32_16x16x32_bf16 v[78:81], v[152:155], v[220:223], v[78:81]
	v_mfma_f32_16x16x32_bf16 v[74:77], v[160:163], v[220:223], v[74:77]
	v_mfma_f32_16x16x32_bf16 v[126:129], v[156:159], v[188:191], v[126:129]
	v_mfma_f32_16x16x32_bf16 v[122:125], v[164:167], v[188:191], v[122:125]
	v_mfma_f32_16x16x32_bf16 v[110:113], v[156:159], v[208:211], v[110:113]
	v_mfma_f32_16x16x32_bf16 v[106:109], v[164:167], v[208:211], v[106:109]
	v_mfma_f32_16x16x32_bf16 v[94:97], v[156:159], v[216:219], v[94:97]
	v_mfma_f32_16x16x32_bf16 v[90:93], v[164:167], v[216:219], v[90:93]
	v_mfma_f32_16x16x32_bf16 v[78:81], v[156:159], v[224:227], v[78:81]
	v_mfma_f32_16x16x32_bf16 v[74:77], v[164:167], v[224:227], v[74:77]
	s_setprio 0
	s_setprio 1
	v_mfma_f32_16x16x32_bf16 v[118:121], v[168:171], v[184:187], v[118:121]
	v_mfma_f32_16x16x32_bf16 v[114:117], v[176:179], v[184:187], v[114:117]
	v_mfma_f32_16x16x32_bf16 v[102:105], v[168:171], v[204:207], v[102:105]
	v_mfma_f32_16x16x32_bf16 v[98:101], v[176:179], v[204:207], v[98:101]
	v_mfma_f32_16x16x32_bf16 v[86:89], v[168:171], v[212:215], v[86:89]
	v_mfma_f32_16x16x32_bf16 v[82:85], v[176:179], v[212:215], v[82:85]
	v_mfma_f32_16x16x32_bf16 v[70:73], v[168:171], v[220:223], v[70:73]
	v_mfma_f32_16x16x32_bf16 v[66:69], v[176:179], v[220:223], v[66:69]
	v_mfma_f32_16x16x32_bf16 v[118:121], v[172:175], v[188:191], v[118:121]
	v_mfma_f32_16x16x32_bf16 v[114:117], v[180:183], v[188:191], v[114:117]
	v_mfma_f32_16x16x32_bf16 v[102:105], v[172:175], v[208:211], v[102:105]
	v_mfma_f32_16x16x32_bf16 v[98:101], v[180:183], v[208:211], v[98:101]
	v_mfma_f32_16x16x32_bf16 v[86:89], v[172:175], v[216:219], v[86:89]
	v_mfma_f32_16x16x32_bf16 v[82:85], v[180:183], v[216:219], v[82:85]
	v_mfma_f32_16x16x32_bf16 v[70:73], v[172:175], v[224:227], v[70:73]
	v_mfma_f32_16x16x32_bf16 v[66:69], v[180:183], v[224:227], v[66:69]
	s_setprio 0
	s_barrier
; #define STAGE(bufoff, GB) do { const char* g_ = (GB); \
;         _Pragma("unroll") for (int i_ = 0; i_ < 2; ++i_) __builtin_amdgcn_global_load_lds((const unsigned*)(g_ + voff[i_]), (LAS3 unsigned*)(L + (bufoff) + stoff + i_ * 8192), 16, 0, 0); } while (0)
; #define LDA(dst, b, h) do { _Pragma("unroll") for (int m = 0; m < 4; ++m) _Pragma("unroll") for (int k = 0; k < 2; ++k) dst[m][k] = *(const LAS3 bf16x8*)(L + SA(b, h) + aoff + m * 2048 + k * 1024); } while (0)
; #define WAIT_V(n) asm volatile("s_waitcnt vmcnt(" #n ")" ::: "memory")
; #define WAIT_L(n) asm volatile("s_waitcnt lgkmcnt(" #n ")" ::: "memory")
; #define BAR __builtin_amdgcn_s_barrier()
; #define SCHED __builtin_amdgcn_sched_barrier(0)
; template <int EPI>
; DI void gemm_phase(const bf16_t* __restrict__ A, const bf16_t* __restrict__ Bt, const int K, const int N, const Params& p, const int layer_j, char* lds) {
;     ...
;             LDA(At, 1, 1); STAGE(SB(1, 0), b3); STAGE(SB(1, 1), b3 + hstep); STAGE(SA(1, 0), a3);
;             WAIT_V(8); WAIT_L(0); BAR; MMA(1, 0, At, B0); MMA(1, 1, At, B1); BAR; SCHED;
;         }
	v_readfirstlane_b32 s18, v146
	v_lshl_add_u64 v[192:193], v[192:193], 0, s[94:95]
	s_mov_b32 m0, s18
	v_readfirstlane_b32 s18, v147
	ds_read_b128 v[184:187], v137 offset:49152
	ds_read_b128 v[188:191], v137 offset:50176
	ds_read_b128 v[204:207], v137 offset:51200
	ds_read_b128 v[208:211], v137 offset:52224
	ds_read_b128 v[212:215], v137 offset:53248
	ds_read_b128 v[216:219], v137 offset:54272
	ds_read_b128 v[220:223], v137 offset:55296
	ds_read_b128 v[224:227], v137 offset:56320
	global_load_lds_dwordx4 v[192:193], off
	v_lshl_add_u64 v[192:193], v[194:195], 0, s[94:95]
	s_mov_b32 m0, s18
	v_readfirstlane_b32 s18, v150
	global_load_lds_dwordx4 v[192:193], off
	v_lshl_add_u64 v[192:193], v[228:229], 0, s[94:95]
	s_mov_b32 m0, s18
	v_readfirstlane_b32 s18, v151
	global_load_lds_dwordx4 v[192:193], off
	v_lshl_add_u64 v[192:193], v[230:231], 0, s[94:95]
	s_mov_b32 m0, s18
	v_readfirstlane_b32 s18, v148
	global_load_lds_dwordx4 v[192:193], off
	v_lshl_add_u64 v[192:193], v[232:233], 0, s[94:95]
	s_mov_b32 m0, s18
	v_readfirstlane_b32 s18, v149
	global_load_lds_dwordx4 v[192:193], off
	v_lshl_add_u64 v[192:193], v[234:235], 0, s[94:95]
	s_mov_b32 m0, s18
	s_nop 0
	global_load_lds_dwordx4 v[192:193], off
	s_waitcnt vmcnt(8)
	s_waitcnt lgkmcnt(0)
	s_barrier
	s_setprio 1
	s_waitcnt lgkmcnt(0)
	v_mfma_f32_16x16x32_bf16 v[62:65], v[152:155], v[184:187], v[62:65]
	v_mfma_f32_16x16x32_bf16 v[58:61], v[160:163], v[184:187], v[58:61]
	v_mfma_f32_16x16x32_bf16 v[38:41], v[152:155], v[204:207], v[38:41]
	v_mfma_f32_16x16x32_bf16 v[24:27], v[160:163], v[204:207], v[24:27]
	v_mfma_f32_16x16x32_bf16 v[12:15], v[152:155], v[212:215], v[12:15]
	v_mfma_f32_16x16x32_bf16 v[8:11], v[160:163], v[212:215], v[8:11]
	v_mfma_f32_16x16x32_bf16 v[4:7], v[152:155], v[220:223], v[4:7]
	v_mfma_f32_16x16x32_bf16 v[0:3], v[160:163], v[220:223], v[0:3]
	v_mfma_f32_16x16x32_bf16 v[62:65], v[156:159], v[188:191], v[62:65]
	v_mfma_f32_16x16x32_bf16 v[58:61], v[164:167], v[188:191], v[58:61]
	v_mfma_f32_16x16x32_bf16 v[38:41], v[156:159], v[208:211], v[38:41]
	v_mfma_f32_16x16x32_bf16 v[24:27], v[164:167], v[208:211], v[24:27]
	v_mfma_f32_16x16x32_bf16 v[12:15], v[156:159], v[216:219], v[12:15]
	v_mfma_f32_16x16x32_bf16 v[8:11], v[164:167], v[216:219], v[8:11]
	v_mfma_f32_16x16x32_bf16 v[4:7], v[156:159], v[224:227], v[4:7]
	v_mfma_f32_16x16x32_bf16 v[0:3], v[164:167], v[224:227], v[0:3]
	s_setprio 0
	s_setprio 1
	v_mfma_f32_16x16x32_bf16 v[46:49], v[168:171], v[184:187], v[46:49]
	v_mfma_f32_16x16x32_bf16 v[42:45], v[176:179], v[184:187], v[42:45]
	v_mfma_f32_16x16x32_bf16 v[20:23], v[168:171], v[204:207], v[20:23]
	v_mfma_f32_16x16x32_bf16 v[16:19], v[176:179], v[204:207], v[16:19]
	v_mfma_f32_16x16x32_bf16 v[50:53], v[168:171], v[212:215], v[50:53]
	v_mfma_f32_16x16x32_bf16 v[54:57], v[176:179], v[212:215], v[54:57]
	v_mfma_f32_16x16x32_bf16 v[28:31], v[168:171], v[220:223], v[28:31]
	v_mfma_f32_16x16x32_bf16 v[34:37], v[176:179], v[220:223], v[34:37]
	v_mfma_f32_16x16x32_bf16 v[46:49], v[172:175], v[188:191], v[46:49]
	v_mfma_f32_16x16x32_bf16 v[42:45], v[180:183], v[188:191], v[42:45]
	v_mfma_f32_16x16x32_bf16 v[20:23], v[172:175], v[208:211], v[20:23]
	v_mfma_f32_16x16x32_bf16 v[16:19], v[180:183], v[208:211], v[16:19]
	v_mfma_f32_16x16x32_bf16 v[50:53], v[172:175], v[216:219], v[50:53]
	v_mfma_f32_16x16x32_bf16 v[54:57], v[180:183], v[216:219], v[54:57]
	v_mfma_f32_16x16x32_bf16 v[28:31], v[172:175], v[224:227], v[28:31]
	v_mfma_f32_16x16x32_bf16 v[34:37], v[180:183], v[224:227], v[34:37]
	s_setprio 0
	s_barrier
	s_add_u32 s37, s37, 0x100
	s_addc_u32 s38, s38, 0
	s_add_u32 s16, s16, 0x100
	s_addc_u32 s17, s17, 0
	s_cmp_ge_u32 s39, s24
	s_mov_b32 s18, s39
	s_cbranch_scc0 .LBB0_106
	v_readlane_b32 s16, v254, 12
	v_readlane_b32 s17, v254, 13
	s_and_b64 vcc, exec, s[16:17]
	s_movk_i32 s37, 0x580
	s_cbranch_vccz .LBB0_109
	s_barrier
; DI int olane() { int l; asm volatile("v_mbcnt_lo_u32_b32 %0, -1, 0\n\tv_mbcnt_hi_u32_b32 %0, -1, %0" : "=v"(l)); return l; }
; DI bf16_t f2bf(float a) { return (bf16_t)(pk_bf16(a, 0.f) & 0xffffu); }
; template <int EPI>
; DI void gemm_phase(const bf16_t* __restrict__ A, const bf16_t* __restrict__ Bt, const int K, const int N, const Params& p, const int layer_j, char* lds) {
;     ...
;         const int le = olane(), fr = le & 15, fq = le >> 4;
;         const int row0 = pm * 256 + wr * 64 + fq * 4;
;         const int col0 = pn * 256 + wc * 64;
;         if (EPI == EPI_F32) {
;             bf16_t* T = (bf16_t*)(ws + OFF_T) + (size_t)row0 * DM + col0 + fr;
; #pragma unroll
;             for (int ai = 0; ai < 2; ++ai)
; #pragma unroll
;                 for (int m = 0; m < 4; ++m)
; #pragma unroll
;                     for (int j = 0; j < 4; ++j)
; #pragma unroll
;                         for (int bj = 0; bj < 2; ++bj)
; #pragma unroll
;                             for (int n = 0; n < 2; ++n) T[(size_t)(ai * 128 + m * 16 + j) * DM + bj * 32 + n * 16] = f2bf(acc[ai][bj][m][n][j]);
.LBB0_109:
	v_mbcnt_lo_u32_b32 v152, -1, 0
	v_mbcnt_hi_u32_b32 v152, -1, v152
	s_mul_i32 s16, s71, 34
	s_add_i32 s16, s16, 0x20100
	v_and_b32_e32 v153, 15, v152
	v_lshrrev_b32_e32 v154, 4, v152
	v_mul_u32_u24_e32 v153, 136, v153
	v_lshl_add_u32 v153, v154, 3, v153
	v_add_u32_e32 v153, s16, v153
	v_lshrrev_b32_e32 v155, 3, v152
	v_and_b32_e32 v156, 7, v152
	v_mul_u32_u24_e32 v154, 136, v155
	v_lshl_add_u32 v154, v156, 4, v154
	v_add_u32_e32 v154, s16, v154
	v_readlane_b32 s16, v254, 7
	v_readlane_b32 s17, v254, 14
	v_lshlrev_b32_e32 v156, 4, v156
	v_add_u32_e32 v155, s16, v155
	v_lshl_add_u32 v155, v155, 11, v156
	s_lshl_b32 s17, s17, 1
	v_add_u32_e32 v155, s17, v155
	v_add_u32_e32 v156, 0x4000, v155
	s_lshl_b32 s16, s34, 19
	s_lshl_b32 s17, s31, 9
	s_add_u32 s16, s16, s17
	s_add_u32 s16, s8, s16
	s_addc_u32 s17, s9, 0
	v_cvt_pk_bf16_f32 v160, v126, v127
	v_cvt_pk_bf16_f32 v161, v128, v129
	v_cvt_pk_bf16_f32 v162, v122, v123
	v_cvt_pk_bf16_f32 v163, v124, v125
	v_cvt_pk_bf16_f32 v164, v118, v119
	v_cvt_pk_bf16_f32 v165, v120, v121
	v_cvt_pk_bf16_f32 v166, v114, v115
	v_cvt_pk_bf16_f32 v167, v116, v117
	ds_write_b64 v153, v[160:161]
	ds_write_b64 v153, v[162:163] offset:32
	ds_write_b64 v153, v[164:165] offset:64
	ds_write_b64 v153, v[166:167] offset:96
	ds_read2_b64 v[168:171], v154 offset1:1
	ds_read2_b64 v[172:175], v154 offset0:136 offset1:137
	s_waitcnt lgkmcnt(0)
	global_store_dwordx4 v155, v[168:171], s[16:17]
	global_store_dwordx4 v156, v[172:175], s[16:17]
	v_cvt_pk_bf16_f32 v160, v110, v111
	v_cvt_pk_bf16_f32 v161, v112, v113
	v_cvt_pk_bf16_f32 v162, v106, v107
	v_cvt_pk_bf16_f32 v163, v108, v109
	v_cvt_pk_bf16_f32 v164, v102, v103
	v_cvt_pk_bf16_f32 v165, v104, v105
	v_cvt_pk_bf16_f32 v166, v98, v99
	v_cvt_pk_bf16_f32 v167, v100, v101
	ds_write_b64 v153, v[160:161]
	ds_write_b64 v153, v[162:163] offset:32
	ds_write_b64 v153, v[164:165] offset:64
	ds_write_b64 v153, v[166:167] offset:96
	ds_read2_b64 v[168:171], v154 offset1:1
	ds_read2_b64 v[172:175], v154 offset0:136 offset1:137
	v_add_u32_e32 v157, 0x8000, v155
	v_add_u32_e32 v158, 0x8000, v156
	s_waitcnt lgkmcnt(0)
	global_store_dwordx4 v157, v[168:171], s[16:17]
	global_store_dwordx4 v158, v[172:175], s[16:17]
	v_cvt_pk_bf16_f32 v160, v94, v95
	v_cvt_pk_bf16_f32 v161, v96, v97
	v_cvt_pk_bf16_f32 v162, v90, v91
	v_cvt_pk_bf16_f32 v163, v92, v93
	v_cvt_pk_bf16_f32 v164, v86, v87
	v_cvt_pk_bf16_f32 v165, v88, v89
	v_cvt_pk_bf16_f32 v166, v82, v83
	v_cvt_pk_bf16_f32 v167, v84, v85
	ds_write_b64 v153, v[160:161]
	ds_write_b64 v153, v[162:163] offset:32
	ds_write_b64 v153, v[164:165] offset:64
	ds_write_b64 v153, v[166:167] offset:96
	ds_read2_b64 v[168:171], v154 offset1:1
	ds_read2_b64 v[172:175], v154 offset0:136 offset1:137
	v_add_u32_e32 v157, 0x10000, v155
	v_add_u32_e32 v158, 0x10000, v156
	s_waitcnt lgkmcnt(0)
	global_store_dwordx4 v157, v[168:171], s[16:17]
	global_store_dwordx4 v158, v[172:175], s[16:17]
	v_cvt_pk_bf16_f32 v160, v78, v79
	v_cvt_pk_bf16_f32 v161, v80, v81
	v_cvt_pk_bf16_f32 v162, v74, v75
	v_cvt_pk_bf16_f32 v163, v76, v77
	v_cvt_pk_bf16_f32 v164, v70, v71
	v_cvt_pk_bf16_f32 v165, v72, v73
	v_cvt_pk_bf16_f32 v166, v66, v67
	v_cvt_pk_bf16_f32 v167, v68, v69
	ds_write_b64 v153, v[160:161]
	ds_write_b64 v153, v[162:163] offset:32
	ds_write_b64 v153, v[164:165] offset:64
	ds_write_b64 v153, v[166:167] offset:96
	ds_read2_b64 v[168:171], v154 offset1:1
	ds_read2_b64 v[172:175], v154 offset0:136 offset1:137
	v_add_u32_e32 v157, 0x18000, v155
	v_add_u32_e32 v158, 0x18000, v156
	s_waitcnt lgkmcnt(0)
	global_store_dwordx4 v157, v[168:171], s[16:17]
	global_store_dwordx4 v158, v[172:175], s[16:17]
	v_cvt_pk_bf16_f32 v160, v62, v63
	v_cvt_pk_bf16_f32 v161, v64, v65
	v_cvt_pk_bf16_f32 v162, v58, v59
	v_cvt_pk_bf16_f32 v163, v60, v61
	v_cvt_pk_bf16_f32 v164, v46, v47
	v_cvt_pk_bf16_f32 v165, v48, v49
	v_cvt_pk_bf16_f32 v166, v42, v43
	v_cvt_pk_bf16_f32 v167, v44, v45
	ds_write_b64 v153, v[160:161]
	ds_write_b64 v153, v[162:163] offset:32
	ds_write_b64 v153, v[164:165] offset:64
	ds_write_b64 v153, v[166:167] offset:96
	ds_read2_b64 v[168:171], v154 offset1:1
	ds_read2_b64 v[172:175], v154 offset0:136 offset1:137
	v_add_u32_e32 v157, 0x40000, v155
	v_add_u32_e32 v158, 0x40000, v156
	s_waitcnt lgkmcnt(0)
	global_store_dwordx4 v157, v[168:171], s[16:17]
	global_store_dwordx4 v158, v[172:175], s[16:17]
	v_cvt_pk_bf16_f32 v160, v38, v39
	v_cvt_pk_bf16_f32 v161, v40, v41
	v_cvt_pk_bf16_f32 v162, v24, v25
	v_cvt_pk_bf16_f32 v163, v26, v27
	v_cvt_pk_bf16_f32 v164, v20, v21
	v_cvt_pk_bf16_f32 v165, v22, v23
	v_cvt_pk_bf16_f32 v166, v16, v17
	v_cvt_pk_bf16_f32 v167, v18, v19
	ds_write_b64 v153, v[160:161]
	ds_write_b64 v153, v[162:163] offset:32
	ds_write_b64 v153, v[164:165] offset:64
	ds_write_b64 v153, v[166:167] offset:96
	ds_read2_b64 v[168:171], v154 offset1:1
	ds_read2_b64 v[172:175], v154 offset0:136 offset1:137
	v_add_u32_e32 v157, 0x48000, v155
	v_add_u32_e32 v158, 0x48000, v156
	s_waitcnt lgkmcnt(0)
	global_store_dwordx4 v157, v[168:171], s[16:17]
	global_store_dwordx4 v158, v[172:175], s[16:17]
	v_cvt_pk_bf16_f32 v160, v12, v13
	v_cvt_pk_bf16_f32 v161, v14, v15
	v_cvt_pk_bf16_f32 v162, v8, v9
	v_cvt_pk_bf16_f32 v163, v10, v11
	v_cvt_pk_bf16_f32 v164, v50, v51
	v_cvt_pk_bf16_f32 v165, v52, v53
	v_cvt_pk_bf16_f32 v166, v54, v55
	v_cvt_pk_bf16_f32 v167, v56, v57
	ds_write_b64 v153, v[160:161]
	ds_write_b64 v153, v[162:163] offset:32
	ds_write_b64 v153, v[164:165] offset:64
	ds_write_b64 v153, v[166:167] offset:96
	ds_read2_b64 v[168:171], v154 offset1:1
	ds_read2_b64 v[172:175], v154 offset0:136 offset1:137
	v_add_u32_e32 v157, 0x50000, v155
	v_add_u32_e32 v158, 0x50000, v156
	s_waitcnt lgkmcnt(0)
	global_store_dwordx4 v157, v[168:171], s[16:17]
	global_store_dwordx4 v158, v[172:175], s[16:17]
	v_cvt_pk_bf16_f32 v160, v4, v5
	v_cvt_pk_bf16_f32 v161, v6, v7
	v_cvt_pk_bf16_f32 v162, v0, v1
	v_cvt_pk_bf16_f32 v163, v2, v3
	v_cvt_pk_bf16_f32 v164, v28, v29
	v_cvt_pk_bf16_f32 v165, v30, v31
	v_cvt_pk_bf16_f32 v166, v34, v35
	v_cvt_pk_bf16_f32 v167, v36, v37
	ds_write_b64 v153, v[160:161]
	ds_write_b64 v153, v[162:163] offset:32
	ds_write_b64 v153, v[164:165] offset:64
	ds_write_b64 v153, v[166:167] offset:96
	ds_read2_b64 v[168:171], v154 offset1:1
	ds_read2_b64 v[172:175], v154 offset0:136 offset1:137
	v_add_u32_e32 v157, 0x58000, v155
	v_add_u32_e32 v158, 0x58000, v156
	s_waitcnt lgkmcnt(0)
	global_store_dwordx4 v157, v[168:171], s[16:17]
	global_store_dwordx4 v158, v[172:175], s[16:17]
	s_andn2_b64 vcc, exec, s[10:11]
	s_mov_b64 s[10:11], -1
	s_mov_b32 s39, 0x2e8ba2e9
	s_cbranch_vccnz .LBB0_98
	s_and_b64 vcc, exec, s[4:5]
	s_cbranch_vccnz .LBB0_97
	s_barrier
	s_branch .LBB0_97

; DI int obid() { int b = blockIdx.x; asm volatile("" : "+s"(b)); return b; }
; template <int EPI>
; DI void gemm_phase(const bf16_t* __restrict__ A, const bf16_t* __restrict__ Bt, const int K, const int N, const Params& p, const int layer_j, char* lds) {
;     ...
;     if (obid() >= nwg) return;
;     int pm, pn;
;     TILE_COORDS(obid(), pm, pn);
.LBB0_336:
	s_ashr_i32 s5, s5, 3
	s_add_i32 s5, s22, s5
	s_ashr_i32 s9, s5, 31
	s_lshr_b32 s9, s9, 28
	s_add_i32 s9, s5, s9
	s_ashr_i32 s20, s9, 4
	s_and_b32 s9, s9, -16
	s_sub_i32 s22, s5, s9
	s_lshl_b32 s5, s66, 2
	s_add_i32 s22, s22, s5
	s_and_b32 s22, s22, 15

; __global__ void __launch_bounds__(NTHREADS) fwd_kernel(Params p) {
;     __shared__ __attribute__((aligned(16))) char lds[LDS_BYTES];
;     cg::grid_group grid = cg::this_grid();
;     __shared__ __attribute__((aligned(16))) unsigned xb_words[4];
	.amdhsa_kernel _Z10fwd_kernel6Params
		.amdhsa_group_segment_fixed_size 163840
		.amdhsa_private_segment_fixed_size 0
		.amdhsa_kernarg_size 384
		.amdhsa_user_sgpr_count 2
		.amdhsa_user_sgpr_dispatch_ptr 0
		.amdhsa_user_sgpr_queue_ptr 0
		.amdhsa_user_sgpr_kernarg_segment_ptr 1
		.amdhsa_user_sgpr_dispatch_id 0
		.amdhsa_user_sgpr_kernarg_preload_length 0
		.amdhsa_user_sgpr_kernarg_preload_offset 0
		.amdhsa_user_sgpr_private_segment_size 0
		.amdhsa_uses_dynamic_stack 0
		.amdhsa_enable_private_segment 0
		.amdhsa_system_sgpr_workgroup_id_x 1
		.amdhsa_system_sgpr_workgroup_id_y 0
		.amdhsa_system_sgpr_workgroup_id_z 0
		.amdhsa_system_sgpr_workgroup_info 0
		.amdhsa_system_vgpr_workitem_id 2
		.amdhsa_next_free_vgpr 256
		.amdhsa_next_free_sgpr 100
		.amdhsa_accum_offset 256
		.amdhsa_reserve_vcc 1
		.amdhsa_float_round_mode_32 0
		.amdhsa_float_round_mode_16_64 0
		.amdhsa_float_denorm_mode_32 3
		.amdhsa_float_denorm_mode_16_64 3
		.amdhsa_dx10_clamp 1
		.amdhsa_ieee_mode 1
		.amdhsa_fp16_overflow 0
		.amdhsa_tg_split 0
		.amdhsa_exception_fp_ieee_invalid_op 0
		.amdhsa_exception_fp_denorm_src 0
		.amdhsa_exception_fp_ieee_div_zero 0
		.amdhsa_exception_fp_ieee_overflow 0
		.amdhsa_exception_fp_ieee_underflow 0
		.amdhsa_exception_fp_ieee_inexact 0
		.amdhsa_exception_int_div_zero 0
	.end_amdhsa_kernel

; __global__ void __launch_bounds__(NTHREADS) fwd_kernel(Params p) {
;     __shared__ __attribute__((aligned(16))) char lds[LDS_BYTES];
;     cg::grid_group grid = cg::this_grid();
;     __shared__ __attribute__((aligned(16))) unsigned xb_words[4];
amdhsa.kernels:
  - .agpr_count:     0
    .args:
      - .offset:         0
        .size:           128
        .value_kind:     by_value
      - .offset:         128
        .size:           4
        .value_kind:     hidden_block_count_x
      - .offset:         132
        .size:           4
        .value_kind:     hidden_block_count_y
      - .offset:         136
        .size:           4
        .value_kind:     hidden_block_count_z
      - .offset:         140
        .size:           2
        .value_kind:     hidden_group_size_x
      - .offset:         142
        .size:           2
        .value_kind:     hidden_group_size_y
      - .offset:         144
        .size:           2
        .value_kind:     hidden_group_size_z
      - .offset:         146
        .size:           2
        .value_kind:     hidden_remainder_x
      - .offset:         148
        .size:           2
        .value_kind:     hidden_remainder_y
      - .offset:         150
        .size:           2
        .value_kind:     hidden_remainder_z
      - .offset:         168
        .size:           8
        .value_kind:     hidden_global_offset_x
      - .offset:         176
        .size:           8
        .value_kind:     hidden_global_offset_y
      - .offset:         184
        .size:           8
        .value_kind:     hidden_global_offset_z
      - .offset:         192
        .size:           2
        .value_kind:     hidden_grid_dims
      - .offset:         216
        .size:           8
        .value_kind:     hidden_multigrid_sync_arg
    .group_segment_fixed_size: 163840
    .kernarg_segment_align: 8
    .kernarg_segment_size: 384
    .language:       OpenCL C
    .language_version:
      - 2
      - 0
    .max_flat_workgroup_size: 512
    .name:           _Z10fwd_kernel6Params
    .private_segment_fixed_size: 0
    .sgpr_count:     106
    .sgpr_spill_count: 98
    .symbol:         _Z10fwd_kernel6Params.kd
    .uniform_work_group_size: 1
    .uses_dynamic_stack: false
    .vgpr_count:     256
    .vgpr_spill_count: 0
    .wavefront_size: 64
